# rwkv_wy<true> prep stage: gate-LoRA column operand (global memory) requested for all four tiles with the first tile's loads instead of nine serialized load groups
# baseline (speedup 1.0000x reference)
.LBB0_852:
	s_or_saveexec_b64 s[0:1], s[44:45]
	v_mov_b32_e32 v98, 0
	v_mov_b32_e32 v99, 0
	v_mov_b32_e32 v94, 0
	v_mov_b32_e32 v95, 0
	v_mov_b32_e32 v102, 0
	v_mov_b32_e32 v103, 0
	v_mov_b32_e32 v100, 0
	v_mov_b32_e32 v101, 0
	v_mov_b32_e32 v142, 0
	v_mov_b32_e32 v143, 0
	v_mov_b32_e32 v120, 0
	v_mov_b32_e32 v121, 0
	v_mov_b32_e32 v108, 0
	v_mov_b32_e32 v109, 0
	v_mov_b32_e32 v104, 0
	v_mov_b32_e32 v105, 0
	v_mov_b32_e32 v152, 0
	v_mov_b32_e32 v153, 0
	v_mov_b32_e32 v96, 0
	v_mov_b32_e32 v97, 0
	v_mov_b32_e32 v148, 0
	v_mov_b32_e32 v149, 0
	v_mov_b32_e32 v146, 0
	v_mov_b32_e32 v147, 0
	v_mov_b32_e32 v144, 0
	v_mov_b32_e32 v145, 0
	v_mov_b32_e32 v122, 0
	v_mov_b32_e32 v123, 0
	v_mov_b32_e32 v110, 0
	v_mov_b32_e32 v111, 0
	v_mov_b32_e32 v106, 0
	v_mov_b32_e32 v107, 0
	s_xor_b64 exec, exec, s[0:1]
	s_cbranch_execz .LBB0_854
	v_lshlrev_b32_e32 v66, 4, v202
	v_or_b32_e32 v0, v66, v192
	v_mul_lo_u32 v0, v0, s6
	v_lshlrev_b32_e32 v2, 4, v194
	v_readlane_b32 s4, v254, 52
	v_mov_b32_e32 v3, v1
	s_mul_i32 s10, s74, 0x3000
	v_add3_u32 v67, s4, v0, v2
	v_mul_u32_u24_e32 v0, 0x60, v192
	v_readlane_b32 s4, v253, 3
	v_lshlrev_b32_e32 v0, 1, v0
	v_readlane_b32 s5, v253, 4
	ds_read_b128 v[76:79], v67
	ds_read_b128 v[80:83], v67 offset:64
	v_lshl_add_u64 v[64:65], s[4:5], 0, v[0:1]
	v_lshl_add_u64 v[154:155], v[64:65], 0, v[2:3]
	v_lshl_add_u64 v[2:3], v[154:155], 0, s[10:11]
	ds_read_b128 v[92:95], v67 offset:192
	ds_read_b128 v[88:91], v67 offset:256
	ds_read_b128 v[84:87], v67 offset:320
	global_load_dwordx4 v[68:71], v[2:3], off
	global_load_dwordx4 v[96:99], v[2:3], off offset:64
	global_load_dwordx4 v[212:215], v[2:3], off offset:128
	s_mov_b64 s[40:41], 0xc00
	v_lshl_add_u64 v[250:251], v[2:3], 0, s[40:41]
	global_load_dwordx4 v[216:219], v[250:251], off
	global_load_dwordx4 v[220:223], v[250:251], off offset:64
	global_load_dwordx4 v[224:227], v[250:251], off offset:128
	s_mov_b64 s[40:41], 0x1800
	v_lshl_add_u64 v[250:251], v[2:3], 0, s[40:41]
	global_load_dwordx4 v[228:231], v[250:251], off
	global_load_dwordx4 v[232:235], v[250:251], off offset:64
	global_load_dwordx4 v[236:239], v[250:251], off offset:128
	s_mov_b64 s[40:41], 0x2400
	v_lshl_add_u64 v[250:251], v[2:3], 0, s[40:41]
	global_load_dwordx4 v[240:243], v[250:251], off
	global_load_dwordx4 v[244:247], v[250:251], off offset:64
	global_load_dwordx4 v[248:251], v[250:251], off offset:128
	v_readlane_b32 s40, v252, 18
	v_readlane_b32 s44, v252, 22
	v_readlane_b32 s45, v252, 23
	v_readlane_b32 s46, v252, 24
	v_readlane_b32 s47, v252, 25
	v_readlane_b32 s48, v252, 26
	v_readlane_b32 s49, v252, 27
	v_readlane_b32 s50, v252, 28
	v_readlane_b32 s51, v252, 29
	s_mov_b64 s[44:45], s[48:49]
	s_mov_b64 s[46:47], s[50:51]
	s_waitcnt lgkmcnt(4)
	v_mfma_f32_16x16x32_bf16 v[72:75], v[76:79], v[24:27], 0
	v_lshl_or_b32 v0, v194, 2, v66
	v_mul_lo_u32 v0, v0, s13
	v_add_u32_e32 v132, 0xc800, v116
	s_waitcnt lgkmcnt(3)
	v_mfma_f32_16x16x32_bf16 v[64:67], v[80:83], v[20:23], 0
	v_add_u32_e32 v133, 0xcc00, v116
	v_add_u32_e32 v136, 0xd400, v116
	v_add_u32_e32 v137, 0xc400, v116
	v_add_u32_e32 v146, 0xd000, v116
	v_add3_u32 v119, 0, v0, v118
	s_mov_b32 s6, 0xbf1b4598
	v_readlane_b32 s41, v252, 19
	v_readlane_b32 s42, v252, 20
	v_readlane_b32 s43, v252, 21
	v_readlane_b32 s52, v252, 30
	v_readlane_b32 s53, v252, 31
	v_readlane_b32 s54, v252, 32
	v_readlane_b32 s55, v252, 33
	s_waitcnt vmcnt(11) lgkmcnt(2)
	v_mfma_f32_16x16x32_bf16 v[68:71], v[92:95], v[68:71], 0
	s_waitcnt vmcnt(10) lgkmcnt(1)
	v_mfma_f32_16x16x32_bf16 v[68:71], v[88:91], v[96:99], v[68:71]
	global_load_dword v108, v190, s[46:47]
	global_load_dword v110, v190, s[46:47] offset:2048
	ds_read2_b32 v[100:101], v132 offset1:16
	ds_read2_b32 v[102:103], v133 offset0:128 offset1:144
	ds_read2_b32 v[130:131], v136 offset1:16
	ds_read2_b32 v[112:113], v137 offset0:128 offset1:144
	ds_read2_b32 v[114:115], v133 offset1:16
	ds_read2_b32 v[116:117], v146 offset0:128 offset1:144
	s_waitcnt vmcnt(2) lgkmcnt(6)
	v_mfma_f32_16x16x32_bf16 v[68:71], v[84:87], v[212:215], v[68:71]
	s_waitcnt vmcnt(1)
	v_add_f32_e32 v2, v72, v108
	v_mul_f32_e32 v2, 0xbfb8aa3b, v2
	v_exp_f32_e32 v97, v2
	s_waitcnt vmcnt(0)
	v_add_f32_e32 v2, v64, v110
	v_mul_f32_e32 v2, 0xbfb8aa3b, v2
	v_exp_f32_e32 v99, v2
	ds_read_u16 v0, v119
	ds_read_u16 v2, v119 offset:32
	s_waitcnt lgkmcnt(3)
	v_mov_b32_e32 v210, v115
	v_mov_b32_e32 v211, v114
	v_mov_b32_e32 v208, v113
	s_waitcnt lgkmcnt(1)
	v_lshlrev_b32_e32 v118, 16, v0
	v_add_f32_e32 v0, v73, v108
	v_mul_f32_e32 v0, 0xbfb8aa3b, v0
	v_exp_f32_e32 v96, v0
	v_mov_b32_e32 v209, v112
	v_pk_add_f32 v[72:73], v[96:97], 1.0 op_sel_hi:[1,0]
	v_rcp_f32_e32 v73, v73
	v_rcp_f32_e32 v72, v72
	v_add_f32_e32 v0, v65, v110
	v_mul_f32_e32 v0, 0xbfb8aa3b, v0
	v_exp_f32_e32 v98, v0
	v_pk_mul_f32 v[104:105], v[72:73], s[6:7] op_sel_hi:[1,0]
	v_pk_add_f32 v[64:65], v[98:99], 1.0 op_sel_hi:[1,0]
	v_rcp_f32_e32 v65, v65
	v_rcp_f32_e32 v64, v64
	ds_read_u16 v0, v119 offset:256
	ds_read_u16 v3, v119 offset:1024
	v_pk_mul_f32 v[106:107], v[64:65], s[6:7] op_sel_hi:[1,0]
	s_waitcnt lgkmcnt(1)
	v_lshlrev_b32_e32 v64, 16, v0
	ds_read_u16 v0, v119 offset:2560
	ds_read_u16 v65, v119 offset:1792
	s_waitcnt lgkmcnt(1)
	v_lshlrev_b32_e32 v73, 16, v0
	s_waitcnt lgkmcnt(0)
	v_lshlrev_b32_e32 v72, 16, v65
	v_lshlrev_b32_e32 v65, 16, v3
	v_mov_b32_e32 v96, v65
	v_mov_b32_e32 v97, v72
	v_pk_mul_f32 v[96:97], v[102:103], v[96:97] op_sel_hi:[0,1]
	v_add_f32_e32 v0, v74, v108
	v_pk_fma_f32 v[64:65], v[100:101], v[64:65], v[96:97] op_sel_hi:[0,1,1]
	v_mul_f32_e32 v0, 0xbfb8aa3b, v0
	v_pk_fma_f32 v[126:127], v[130:131], v[72:73], v[64:65] op_sel_hi:[0,1,1]
	v_exp_f32_e32 v65, v0
	v_add_f32_e32 v0, v66, v110
	v_mul_f32_e32 v0, 0xbfb8aa3b, v0
	v_exp_f32_e32 v97, v0
	ds_read_u16 v0, v119 offset:3072
	s_waitcnt lgkmcnt(0)
	v_lshlrev_b32_e32 v3, 16, v0
	v_add_f32_e32 v0, v75, v108
	v_mul_f32_e32 v0, 0xbfb8aa3b, v0
	v_exp_f32_e32 v64, v0
	s_nop 0
	v_pk_add_f32 v[64:65], v[64:65], 1.0 op_sel_hi:[1,0]
	v_rcp_f32_e32 v65, v65
	v_rcp_f32_e32 v64, v64
	v_add_f32_e32 v0, v67, v110
	v_mul_f32_e32 v0, 0xbfb8aa3b, v0
	v_exp_f32_e32 v96, v0
	v_pk_mul_f32 v[108:109], v[64:65], s[6:7] op_sel_hi:[1,0]
	v_pk_add_f32 v[64:65], v[96:97], 1.0 op_sel_hi:[1,0]
	v_mfma_f32_16x16x32_bf16 v[96:99], v[76:79], v[32:35], 0
	v_rcp_f32_e32 v65, v65
	v_rcp_f32_e32 v64, v64
	s_nop 0
	v_pk_mul_f32 v[110:111], v[64:65], s[6:7] op_sel_hi:[1,0]
	ds_read_u16 v0, v119 offset:4096
	ds_read_u16 v64, v119 offset:3328
	s_waitcnt lgkmcnt(1)
	v_lshlrev_b32_e32 v65, 16, v0
	ds_read_u16 v0, v119 offset:3840
	s_waitcnt lgkmcnt(1)
	v_lshlrev_b32_e32 v64, 16, v64
	v_pk_mov_b32 v[66:67], v[72:73], v[64:65] op_sel:[1,0]
	s_waitcnt lgkmcnt(0)
	v_lshlrev_b32_e32 v153, 16, v0
	v_or_b32_e32 v0, 16, v191
	v_sub_u32_e32 v0, v0, v192
	v_mul_u32_u24_e32 v0, 0x60, v0
	v_pk_mul_f32 v[66:67], v[102:103], v[66:67] op_sel_hi:[0,1]
	v_lshlrev_b32_e32 v0, 1, v0
	v_pk_fma_f32 v[66:67], v[100:101], v[72:73], v[66:67] op_sel_hi:[0,1,1]
	v_lshl_add_u64 v[134:135], v[154:155], 0, v[0:1]
	v_pk_fma_f32 v[128:129], v[130:131], v[64:65], v[66:67] op_sel_hi:[0,1,1]
	v_mfma_f32_16x16x32_bf16 v[72:75], v[80:83], v[28:31], 0
	s_waitcnt vmcnt(1)
	v_mfma_f32_16x16x32_bf16 v[64:67], v[92:95], v[216:219], 0
	s_waitcnt vmcnt(0)
	v_mfma_f32_16x16x32_bf16 v[64:67], v[88:91], v[220:223], v[64:67]
	global_load_dword v130, v201, s[46:47] offset:64
	global_load_dword v138, v201, s[46:47] offset:2112
	s_waitcnt vmcnt(1)
	v_add_f32_e32 v0, v96, v130
	v_mul_f32_e32 v0, 0xbfb8aa3b, v0
	v_mfma_f32_16x16x32_bf16 v[64:67], v[84:87], v[224:227], v[64:67]
	v_exp_f32_e32 v121, v0
	s_waitcnt vmcnt(0)
	v_add_f32_e32 v0, v72, v138
	v_mul_f32_e32 v0, 0xbfb8aa3b, v0
	v_exp_f32_e32 v123, v0
	v_add_f32_e32 v0, v97, v130
	v_mul_f32_e32 v0, 0xbfb8aa3b, v0
	v_exp_f32_e32 v120, v0
	s_nop 0
	v_pk_add_f32 v[96:97], v[120:121], 1.0 op_sel_hi:[1,0]
	v_rcp_f32_e32 v97, v97
	v_rcp_f32_e32 v96, v96
	v_add_f32_e32 v0, v73, v138
	v_mul_f32_e32 v0, 0xbfb8aa3b, v0
	v_exp_f32_e32 v122, v0
	v_pk_mul_f32 v[120:121], v[96:97], s[6:7] op_sel_hi:[1,0]
	v_pk_add_f32 v[72:73], v[122:123], 1.0 op_sel_hi:[1,0]
	v_rcp_f32_e32 v73, v73
	v_rcp_f32_e32 v72, v72
	s_nop 0
	v_pk_mul_f32 v[122:123], v[72:73], s[6:7] op_sel_hi:[1,0]
	ds_read_u16 v0, v119 offset:288
	ds_read_u16 v73, v119 offset:1056
	v_mov_b32_e32 v100, v103
	s_waitcnt lgkmcnt(1)
	v_lshlrev_b32_e32 v72, 16, v0
	ds_read_u16 v0, v119 offset:2592
	ds_read_u16 v96, v119 offset:1824
	s_waitcnt lgkmcnt(2)
	v_lshlrev_b32_e32 v73, 16, v73
	v_mov_b32_e32 v134, v73
	s_waitcnt lgkmcnt(1)
	v_lshlrev_b32_e32 v97, 16, v0
	s_waitcnt lgkmcnt(0)
	v_lshlrev_b32_e32 v96, 16, v96
	v_mov_b32_e32 v135, v96
	v_mov_b32_e32 v0, v101
	v_pk_mul_f32 v[102:103], v[100:101], v[134:135] op_sel_hi:[0,1]
	v_pk_fma_f32 v[72:73], v[0:1], v[72:73], v[102:103] op_sel_hi:[0,1,1]
	v_mov_b32_e32 v102, v131
	v_pk_fma_f32 v[134:135], v[102:103], v[96:97], v[72:73] op_sel_hi:[0,1,1]
	v_add_f32_e32 v72, v98, v130
	v_mul_f32_e32 v72, 0xbfb8aa3b, v72
	v_exp_f32_e32 v73, v72
	v_add_f32_e32 v72, v74, v138
	v_mul_f32_e32 v72, 0xbfb8aa3b, v72
	v_exp_f32_e32 v131, v72
	ds_read_u16 v72, v119 offset:3104
	s_waitcnt lgkmcnt(0)
	v_lshlrev_b32_e32 v167, 16, v72
	v_add_f32_e32 v72, v99, v130
	v_mul_f32_e32 v72, 0xbfb8aa3b, v72
	v_exp_f32_e32 v72, v72
	s_nop 0
	v_pk_add_f32 v[72:73], v[72:73], 1.0 op_sel_hi:[1,0]
	v_rcp_f32_e32 v73, v73
	v_div_scale_f32 v74, s[4:5], v72, v72, 1.0
	v_rcp_f32_e32 v98, v74
	s_nop 0
	v_fma_f32 v99, -v74, v98, 1.0
	v_fmac_f32_e32 v98, v99, v98
	v_div_scale_f32 v99, vcc, 1.0, v72, 1.0
	v_mul_f32_e32 v101, v99, v98
	v_fma_f32 v103, -v74, v101, v99
	v_fmac_f32_e32 v101, v103, v98
	v_fma_f32 v74, -v74, v101, v99
	v_div_fmas_f32 v74, v74, v98, v101
	v_div_fixup_f32 v72, v74, v72, 1.0
	v_pk_mul_f32 v[142:143], v[72:73], s[6:7] op_sel_hi:[1,0]
	v_add_f32_e32 v72, v75, v138
	v_mul_f32_e32 v72, 0xbfb8aa3b, v72
	v_exp_f32_e32 v130, v72
	s_nop 0
	v_pk_add_f32 v[72:73], v[130:131], 1.0 op_sel_hi:[1,0]
	v_rcp_f32_e32 v73, v73
	v_div_scale_f32 v74, s[4:5], v72, v72, 1.0
	v_rcp_f32_e32 v75, v74
	s_nop 0
	v_fma_f32 v98, -v74, v75, 1.0
	v_fmac_f32_e32 v75, v98, v75
	v_div_scale_f32 v98, vcc, 1.0, v72, 1.0
	v_mul_f32_e32 v99, v98, v75
	v_fma_f32 v101, -v74, v99, v98
	v_fmac_f32_e32 v99, v101, v75
	v_fma_f32 v74, -v74, v99, v98
	v_div_fmas_f32 v74, v74, v75, v99
	v_div_fixup_f32 v72, v74, v72, 1.0
	v_pk_mul_f32 v[144:145], v[72:73], s[6:7] op_sel_hi:[1,0]
	ds_read_u16 v73, v119 offset:4128
	ds_read_u16 v72, v119 offset:3360
	s_waitcnt lgkmcnt(1)
	v_lshlrev_b32_e32 v73, 16, v73
	s_waitcnt lgkmcnt(0)
	v_lshlrev_b32_e32 v72, 16, v72
	v_pk_mov_b32 v[74:75], v[96:97], v[72:73] op_sel:[1,0]
	s_nop 0
	v_pk_mul_f32 v[74:75], v[100:101], v[74:75] op_sel_hi:[0,1]
	v_pk_fma_f32 v[74:75], v[0:1], v[96:97], v[74:75] op_sel_hi:[0,1,1]
	ds_read_u16 v0, v119 offset:3872
	v_pk_fma_f32 v[130:131], v[102:103], v[72:73], v[74:75] op_sel_hi:[0,1,1]
	v_mfma_f32_16x16x32_bf16 v[96:99], v[80:83], v[36:39], 0
	s_waitcnt lgkmcnt(0)
	v_lshlrev_b32_e32 v169, 16, v0
	v_or_b32_e32 v0, 32, v191
	v_sub_u32_e32 v0, v0, v192
	v_mul_u32_u24_e32 v0, 0x60, v0
	v_lshlrev_b32_e32 v0, 1, v0
	v_lshl_add_u64 v[148:149], v[154:155], 0, v[0:1]
	s_waitcnt vmcnt(1)
	v_mfma_f32_16x16x32_bf16 v[72:75], v[92:95], v[228:231], 0
	s_waitcnt vmcnt(0)
	v_mfma_f32_16x16x32_bf16 v[72:75], v[88:91], v[232:235], v[72:75]
	global_load_dword v0, v201, s[46:47] offset:128
	global_load_dword v152, v201, s[46:47] offset:2176
	s_waitcnt vmcnt(0)
	v_add_f32_e32 v96, v96, v152
	v_mfma_f32_16x16x32_bf16 v[100:103], v[76:79], v[48:51], 0
	v_mul_f32_e32 v96, 0xbfb8aa3b, v96
	v_exp_f32_e32 v147, v96
	v_mfma_f32_16x16x32_bf16 v[72:75], v[84:87], v[236:239], v[72:75]
	ds_read2_b32 v[158:159], v132 offset0:32 offset1:48
	ds_read2_b32 v[164:165], v133 offset0:160 offset1:176
	ds_read2_b32 v[156:157], v136 offset0:32 offset1:48
	ds_read2_b32 v[140:141], v137 offset0:160 offset1:176
	ds_read2_b32 v[138:139], v133 offset0:32 offset1:48
	ds_read2_b32 v[136:137], v146 offset0:160 offset1:176
	v_add_f32_e32 v100, v100, v0
	v_add_f32_e32 v96, v101, v0
	v_mul_f32_e32 v100, 0xbfb8aa3b, v100
	v_mul_f32_e32 v96, 0xbfb8aa3b, v96
	v_exp_f32_e32 v133, v100
	v_exp_f32_e32 v132, v96
	v_mfma_f32_16x16x32_bf16 v[80:83], v[80:83], v[60:63], 0
	s_waitcnt lgkmcnt(4)
	v_mov_b32_e32 v176, v165
	s_waitcnt lgkmcnt(3)
	v_mov_b32_e32 v178, v157
	v_pk_add_f32 v[100:101], v[132:133], 1.0 op_sel_hi:[1,0]
	v_rcp_f32_e32 v101, v101
	v_rcp_f32_e32 v100, v100
	v_add_f32_e32 v96, v97, v152
	v_mul_f32_e32 v96, 0xbfb8aa3b, v96
	v_exp_f32_e32 v146, v96
	v_pk_mul_f32 v[100:101], v[100:101], s[6:7] op_sel_hi:[1,0]
	v_pk_add_f32 v[96:97], v[146:147], 1.0 op_sel_hi:[1,0]
	v_rcp_f32_e32 v97, v97
	v_rcp_f32_e32 v96, v96
	s_nop 0
	v_pk_mul_f32 v[146:147], v[96:97], s[6:7] op_sel_hi:[1,0]
	ds_read_u16 v96, v119 offset:320
	ds_read_u16 v97, v119 offset:1088
	ds_read_u16 v133, v119 offset:2624
	ds_read_u16 v132, v119 offset:1856
	s_waitcnt lgkmcnt(3)
	v_lshlrev_b32_e32 v96, 16, v96
	s_waitcnt lgkmcnt(2)
	v_lshlrev_b32_e32 v97, 16, v97
	s_waitcnt lgkmcnt(0)
	v_lshlrev_b32_e32 v132, 16, v132
	v_mov_b32_e32 v148, v97
	v_mov_b32_e32 v149, v132
	v_pk_mul_f32 v[148:149], v[164:165], v[148:149] op_sel_hi:[0,1]
	v_lshlrev_b32_e32 v133, 16, v133
	v_pk_fma_f32 v[96:97], v[158:159], v[96:97], v[148:149] op_sel_hi:[0,1,1]
	v_pk_fma_f32 v[150:151], v[156:157], v[132:133], v[96:97] op_sel_hi:[0,1,1]
	v_add_f32_e32 v96, v102, v0
	v_mul_f32_e32 v96, 0xbfb8aa3b, v96
	v_exp_f32_e32 v97, v96
	v_add_f32_e32 v96, v98, v152
	v_mul_f32_e32 v96, 0xbfb8aa3b, v96
	v_exp_f32_e32 v149, v96
	ds_read_u16 v96, v119 offset:3136
	v_add_f32_e32 v0, v103, v0
	v_mul_f32_e32 v0, 0xbfb8aa3b, v0
	s_waitcnt lgkmcnt(0)
	v_lshlrev_b32_e32 v171, 16, v96
	v_exp_f32_e32 v96, v0
	s_nop 0
	v_pk_add_f32 v[96:97], v[96:97], 1.0 op_sel_hi:[1,0]
	v_rcp_f32_e32 v97, v97
	v_rcp_f32_e32 v96, v96
	v_add_f32_e32 v0, v99, v152
	v_mul_f32_e32 v0, 0xbfb8aa3b, v0
	v_exp_f32_e32 v148, v0
	v_pk_mul_f32 v[102:103], v[96:97], s[6:7] op_sel_hi:[1,0]
	v_pk_add_f32 v[96:97], v[148:149], 1.0 op_sel_hi:[1,0]
	v_rcp_f32_e32 v97, v97
	v_rcp_f32_e32 v96, v96
	s_nop 0
	v_pk_mul_f32 v[148:149], v[96:97], s[6:7] op_sel_hi:[1,0]
	ds_read_u16 v0, v119 offset:4160
	ds_read_u16 v96, v119 offset:3392
	s_waitcnt lgkmcnt(1)
	v_lshlrev_b32_e32 v97, 16, v0
	ds_read_u16 v0, v119 offset:3904
	s_waitcnt lgkmcnt(1)
	v_lshlrev_b32_e32 v96, 16, v96
	v_pk_mov_b32 v[98:99], v[132:133], v[96:97] op_sel:[1,0]
	s_waitcnt lgkmcnt(0)
	v_lshlrev_b32_e32 v173, 16, v0
	v_or_b32_e32 v0, 48, v191
	v_sub_u32_e32 v0, v0, v192
	v_mul_u32_u24_e32 v0, 0x60, v0
	v_pk_mul_f32 v[98:99], v[164:165], v[98:99] op_sel_hi:[0,1]
	v_lshlrev_b32_e32 v0, 1, v0
	v_pk_fma_f32 v[98:99], v[158:159], v[132:133], v[98:99] op_sel_hi:[0,1,1]
	v_lshl_add_u64 v[154:155], v[154:155], 0, v[0:1]
	v_pk_fma_f32 v[132:133], v[156:157], v[96:97], v[98:99] op_sel_hi:[0,1,1]
	v_mfma_f32_16x16x32_bf16 v[96:99], v[76:79], v[56:59], 0
	s_waitcnt vmcnt(0)
	v_mfma_f32_16x16x32_bf16 v[76:79], v[92:95], v[240:243], 0
	s_waitcnt vmcnt(0)
	v_mfma_f32_16x16x32_bf16 v[76:79], v[88:91], v[244:247], v[76:79]
	global_load_dword v180, v201, s[46:47] offset:192
	global_load_dword v203, v201, s[46:47] offset:2240
	s_waitcnt vmcnt(1)
	s_nop 0
	v_add_f32_e32 v0, v96, v180
	v_mul_f32_e32 v0, 0xbfb8aa3b, v0
	v_mfma_f32_16x16x32_bf16 v[76:79], v[84:87], v[248:251], v[76:79]
	v_exp_f32_e32 v85, v0
	s_waitcnt vmcnt(0)
	v_add_f32_e32 v0, v80, v203
	v_mul_f32_e32 v0, 0xbfb8aa3b, v0
	v_exp_f32_e32 v87, v0
	v_add_f32_e32 v0, v97, v180
	v_mul_f32_e32 v0, 0xbfb8aa3b, v0
	v_exp_f32_e32 v84, v0
	v_lshlrev_b32_e32 v90, 16, v2
	v_pk_add_f32 v[84:85], v[84:85], 1.0 op_sel_hi:[1,0]
	v_rcp_f32_e32 v85, v85
	v_rcp_f32_e32 v84, v84
	v_add_f32_e32 v0, v81, v203
	v_mul_f32_e32 v0, 0xbfb8aa3b, v0
	v_exp_f32_e32 v86, v0
	v_pk_mul_f32 v[94:95], v[84:85], s[6:7] op_sel_hi:[1,0]
	v_pk_add_f32 v[80:81], v[86:87], 1.0 op_sel_hi:[1,0]
	v_rcp_f32_e32 v81, v81
	v_rcp_f32_e32 v80, v80
	s_nop 0
	v_pk_mul_f32 v[96:97], v[80:81], s[6:7] op_sel_hi:[1,0]
	ds_read_u16 v0, v119 offset:352
	ds_read_u16 v81, v119 offset:1120
	s_waitcnt lgkmcnt(1)
	v_lshlrev_b32_e32 v80, 16, v0
	ds_read_u16 v0, v119 offset:2656
	ds_read_u16 v84, v119 offset:1888
	s_waitcnt lgkmcnt(2)
	v_lshlrev_b32_e32 v81, 16, v81
	s_waitcnt lgkmcnt(1)
	v_lshlrev_b32_e32 v175, 16, v0
	s_waitcnt lgkmcnt(0)
	v_lshlrev_b32_e32 v174, 16, v84
	v_mov_b32_e32 v84, v81
	v_mov_b32_e32 v85, v174
	v_mov_b32_e32 v0, v159
	v_pk_mul_f32 v[84:85], v[176:177], v[84:85] op_sel_hi:[0,1]
	v_pk_fma_f32 v[80:81], v[0:1], v[80:81], v[84:85] op_sel_hi:[0,1,1]
	v_pk_fma_f32 v[154:155], v[178:179], v[174:175], v[80:81] op_sel_hi:[0,1,1]
	v_add_f32_e32 v80, v98, v180
	v_mul_f32_e32 v80, 0xbfb8aa3b, v80
	v_exp_f32_e32 v205, v80
	v_add_f32_e32 v80, v82, v203
	v_mul_f32_e32 v80, 0xbfb8aa3b, v80
	v_exp_f32_e32 v181, v80
	ds_read_u16 v80, v119 offset:864
	ds_read_u16 v81, v119 offset:1632
	v_mov_b32_e32 v98, v115
	s_waitcnt lgkmcnt(1)
	v_lshlrev_b32_e32 v206, 16, v80
	ds_read_u16 v80, v119 offset:3168
	ds_read_u16 v82, v119 offset:2400
	s_waitcnt lgkmcnt(2)
	v_lshlrev_b32_e32 v207, 16, v81
	v_mov_b32_e32 v156, v207
	v_mov_b32_e32 v172, v207
	s_waitcnt lgkmcnt(1)
	v_lshlrev_b32_e32 v159, 16, v80
	s_waitcnt lgkmcnt(0)
	v_lshlrev_b32_e32 v157, 16, v82
	ds_read_u16 v80, v119 offset:96
	ds_read_u16 v81, v119 offset:2368
	ds_read_u16 v82, v119 offset:832
	ds_read_u16 v84, v119 offset:1600
	v_mov_b32_e32 v158, v157
	s_waitcnt lgkmcnt(3)
	v_lshlrev_b32_e32 v80, 16, v80
	s_waitcnt lgkmcnt(2)
	v_lshlrev_b32_e32 v81, 16, v81
	s_waitcnt lgkmcnt(0)
	v_lshlrev_b32_e32 v85, 16, v84
	v_lshlrev_b32_e32 v84, 16, v82
	ds_read_u16 v82, v119 offset:64
	ds_read_u16 v86, v119 offset:2336
	v_mov_b32_e32 v168, v85
	v_mov_b32_e32 v170, v81
	s_waitcnt lgkmcnt(0)
	v_lshlrev_b32_e32 v87, 16, v86
	v_lshlrev_b32_e32 v86, 16, v82
	ds_read_u16 v82, v119 offset:800
	ds_read_u16 v88, v119 offset:1568
	v_mov_b32_e32 v166, v87
	s_waitcnt lgkmcnt(0)
	v_lshlrev_b32_e32 v89, 16, v88
	v_lshlrev_b32_e32 v88, 16, v82
	ds_read_u16 v82, v119 offset:2304
	v_mov_b32_e32 v152, v89
	s_waitcnt lgkmcnt(0)
	v_lshlrev_b32_e32 v91, 16, v82
	ds_read_u16 v2, v119 offset:768
	ds_read_u16 v82, v119 offset:1536
	v_mov_b32_e32 v93, v91
	s_waitcnt lgkmcnt(1)
	v_lshlrev_b32_e32 v164, 16, v2
	s_waitcnt lgkmcnt(0)
	v_lshlrev_b32_e32 v165, 16, v82
	v_mov_b32_e32 v92, v165
	v_pk_mul_f32 v[92:93], v[114:115], v[92:93] op_sel_hi:[0,1]
	v_mov_b32_e32 v2, v91
	v_pk_fma_f32 v[92:93], v[112:113], v[164:165], v[92:93] op_sel_hi:[0,1,1]
	v_pk_fma_f32 v[92:93], v[116:117], v[2:3], v[92:93] op_sel_hi:[0,1,1]
	v_mov_b32_e32 v2, v88
	v_pk_mul_f32 v[2:3], v[210:211], v[2:3]
	v_mov_b32_e32 v82, v117
	v_pk_fma_f32 v[2:3], v[208:209], v[90:91], v[2:3]
	v_mov_b32_e32 v90, v117
	v_mov_b32_e32 v91, v116
	v_pk_fma_f32 v[90:91], v[90:91], v[152:153], v[2:3]
	v_mov_b32_e32 v153, v87
	v_mov_b32_e32 v2, v113
	v_pk_mul_f32 v[152:153], v[98:99], v[152:153] op_sel_hi:[0,1]
	v_pk_fma_f32 v[2:3], v[2:3], v[88:89], v[152:153] op_sel_hi:[0,1,1]
	v_pk_fma_f32 v[88:89], v[82:83], v[166:167], v[2:3] op_sel_hi:[0,1,1]
	v_mov_b32_e32 v152, v138
	v_mov_b32_e32 v153, v115
	v_mov_b32_e32 v166, v84
	v_mov_b32_e32 v2, v140
	v_mov_b32_e32 v3, v113
	v_pk_mul_f32 v[152:153], v[152:153], v[166:167]
	v_mov_b32_e32 v82, v139
	v_pk_fma_f32 v[2:3], v[2:3], v[86:87], v[152:153]
	v_mov_b32_e32 v86, v136
	v_mov_b32_e32 v87, v117
	v_pk_fma_f32 v[86:87], v[86:87], v[168:169], v[2:3]
	v_mov_b32_e32 v2, v85
	v_mov_b32_e32 v3, v81
	v_pk_mul_f32 v[2:3], v[138:139], v[2:3] op_sel_hi:[0,1]
	v_pk_fma_f32 v[2:3], v[140:141], v[84:85], v[2:3] op_sel_hi:[0,1,1]
	v_pk_fma_f32 v[84:85], v[136:137], v[170:171], v[2:3] op_sel_hi:[0,1,1]
	v_mov_b32_e32 v152, v139
	v_mov_b32_e32 v153, v138
	v_mov_b32_e32 v170, v206
	v_mov_b32_e32 v2, v141
	v_mov_b32_e32 v3, v140
	v_pk_mul_f32 v[152:153], v[152:153], v[170:171]
	v_mov_b32_e32 v140, v127
	v_pk_fma_f32 v[2:3], v[2:3], v[80:81], v[152:153]
	v_mov_b32_e32 v80, v137
	v_mov_b32_e32 v81, v136
	v_pk_fma_f32 v[80:81], v[80:81], v[172:173], v[2:3]
	v_mov_b32_e32 v2, v141
	v_pk_mul_f32 v[152:153], v[82:83], v[156:157] op_sel_hi:[0,1]
	v_pk_fma_f32 v[2:3], v[2:3], v[206:207], v[152:153] op_sel_hi:[0,1,1]
	v_mov_b32_e32 v82, v137
	v_pk_fma_f32 v[2:3], v[82:83], v[158:159], v[2:3] op_sel_hi:[0,1,1]
	v_add_f32_e32 v82, v99, v180
	v_mul_f32_e32 v82, 0xbfb8aa3b, v82
	v_exp_f32_e32 v204, v82
	v_mov_b32_e32 v156, v164
	v_pk_add_f32 v[98:99], v[204:205], 1.0 op_sel_hi:[1,0]
	v_rcp_f32_e32 v99, v99
	v_rcp_f32_e32 v98, v98
	v_add_f32_e32 v82, v83, v203
	v_mul_f32_e32 v82, 0xbfb8aa3b, v82
	v_exp_f32_e32 v180, v82
	v_pk_mul_f32 v[98:99], v[98:99], s[6:7] op_sel_hi:[1,0]
	v_pk_add_f32 v[82:83], v[180:181], 1.0 op_sel_hi:[1,0]
	v_rcp_f32_e32 v83, v83
	v_rcp_f32_e32 v82, v82
	s_nop 0
	v_pk_mul_f32 v[152:153], v[82:83], s[6:7] op_sel_hi:[1,0]
	ds_read_u16 v82, v119 offset:4192
	ds_read_u16 v83, v119 offset:3424
	v_mov_b32_e32 v113, v139
	v_mov_b32_e32 v115, v141
	v_mov_b32_e32 v117, v137
	s_waitcnt lgkmcnt(1)
	v_lshlrev_b32_e32 v167, 16, v82
	s_waitcnt lgkmcnt(0)
	v_lshlrev_b32_e32 v166, 16, v83
	v_pk_mov_b32 v[82:83], v[174:175], v[166:167] op_sel:[1,0]
	v_mov_b32_e32 v141, v128
	v_pk_mul_f32 v[82:83], v[176:177], v[82:83] op_sel_hi:[0,1]
	v_pk_fma_f32 v[82:83], v[0:1], v[174:175], v[82:83] op_sel_hi:[0,1,1]
	ds_read_u16 v0, v119 offset:3936
	v_mov_b32_e32 v119, v159
	v_pk_mul_f32 v[112:113], v[112:113], v[118:119]
	v_pk_fma_f32 v[166:167], v[178:179], v[166:167], v[82:83] op_sel_hi:[0,1,1]
	v_pk_fma_f32 v[112:113], v[114:115], v[156:157], v[112:113]
	s_waitcnt lgkmcnt(0)
	v_lshlrev_b32_e32 v83, 16, v0
	v_mov_b32_e32 v82, v165
	v_pk_fma_f32 v[82:83], v[116:117], v[82:83], v[112:113]
	v_mov_b32_e32 v128, v134
	v_mov_b32_e32 v138, v135
	v_mov_b32_e32 v139, v130
	v_mov_b32_e32 v130, v150
	v_mov_b32_e32 v136, v151
	v_mov_b32_e32 v137, v132
	v_mov_b32_e32 v132, v154
	v_mov_b32_e32 v134, v155
	v_mov_b32_e32 v135, v166
	v_mov_b32_e32 v127, v167
